# attention unit epilogue: the 32 per-row scale reads from LDS issued together and waited once (was 16 serialized round trips); plus static priority for the trailing half in GEMM K-loops; stacked on sta
# speedup vs baseline: 1.0065x; 1.0065x over previous
; __device__ __forceinline__ int crow(int r, int hi) { return (r & 3) + 8 * (r >> 2) + 4 * hi; }
; __device__ __forceinline__ unsigned cvtpk_s(float lo, float hi) { f32x2_t v = {lo, hi}; bf16x2_t b = __builtin_convertvector(v, bf16x2_t); return __builtin_bit_cast(unsigned, b); }
; __device__ __forceinline__ float sum8f(float x) { x += dppf<0xB1>(x); x += dppf<0x4E>(x); x += dppf<0x141>(x); return x; }
; #define x (arg_in(0))
;     ...
;     { auto rr = __builtin_amdgcn_permlane32_swap(__float_as_uint(lA), __float_as_uint(lA), false, false); lA = __uint_as_float(rr[0]) + __uint_as_float(rr[1]); }
;     { auto rr = __builtin_amdgcn_permlane32_swap(__float_as_uint(lB), __float_as_uint(lB), false, false); lB = __uint_as_float(rr[0]) + __uint_as_float(rr[1]); }
;     if (hi == 0) { wsf[64 + r32] = 1.f / lA; wsf[96 + r32] = lam / lB; }
;     asm volatile("s_waitcnt lgkmcnt(0)" ::: "memory");
;     float* stg = (float*)(shm + LDS_OST) + wid * 2048;
; #pragma unroll
;     for (int r = 0; r < 16; ++r) { const int orow = crow(r, hi); const float a = wsf[64 + orow], c = wsf[96 + orow];
;         stg[orow * 64 + r32] = oa0[r] * a - ob0[r] * c; stg[orow * 64 + 32 + r32] = oa1[r] * a - ob1[r] * c; }
;     asm volatile("s_waitcnt lgkmcnt(0)" ::: "memory");
;     bf16_t* Ow = mix + (rowbase + q0 + wid * 32) * D + h * 64;
;     const int ch = lane & 7;
;     const float4 g0 = *(const float4*)(gsub + ch * 8), g1 = *(const float4*)(gsub + ch * 8 + 4);
; #pragma unroll
;     for (int i = 0; i < 4; ++i) { const int row = i * 8 + (lane >> 3);
;         const float4 a = *(const float4*)(stg + row * 64 + ch * 8), c = *(const float4*)(stg + row * 64 + ch * 8 + 4);
;         float ss = a.x * a.x + a.y * a.y + a.z * a.z + a.w * a.w + c.x * c.x + c.y * c.y + c.z * c.z + c.w * c.w;
;         ss = sum8f(ss);
;         const float rn = rsqrtf(ss * (1.f / 64.f) + EPS) * oscale;
;         u32x4 w; w.x = cvtpk_s(a.x * rn * g0.x, a.y * rn * g0.y); w.y = cvtpk_s(a.z * rn * g0.z, a.w * rn * g0.w); w.z = cvtpk_s(c.x * rn * g1.x, c.y * rn * g1.y); w.w = cvtpk_s(c.z * rn * g1.z, c.w * rn * g1.w);
;         *(u32x4*)(Ow + (long)row * D + ch * 8) = w; }
.LBB0_372:
	s_or_b64 exec, exec, s[36:37]
	s_waitcnt lgkmcnt(0)
	ds_read_b32 v68, v185 offset:384
	ds_read_b32 v69, v185 offset:256
	ds_read_b32 v70, v185 offset:388
	ds_read_b32 v71, v185 offset:260
	ds_read_b32 v72, v185 offset:392
	ds_read_b32 v73, v185 offset:264
	ds_read_b32 v74, v185 offset:396
	ds_read_b32 v75, v185 offset:268
	ds_read_b32 v76, v185 offset:416
	ds_read_b32 v77, v185 offset:288
	ds_read_b32 v78, v185 offset:420
	ds_read_b32 v79, v185 offset:292
	ds_read_b32 v80, v185 offset:424
	ds_read_b32 v81, v185 offset:296
	ds_read_b32 v82, v185 offset:428
	ds_read_b32 v83, v185 offset:300
	ds_read_b32 v84, v185 offset:448
	ds_read_b32 v85, v185 offset:320
	ds_read_b32 v86, v185 offset:452
	ds_read_b32 v87, v185 offset:324
	ds_read_b32 v88, v185 offset:456
	ds_read_b32 v89, v185 offset:328
	ds_read_b32 v90, v185 offset:460
	ds_read_b32 v91, v185 offset:332
	ds_read_b32 v92, v185 offset:480
	ds_read_b32 v93, v185 offset:352
	ds_read_b32 v94, v185 offset:484
	ds_read_b32 v95, v185 offset:356
	ds_read_b32 v96, v185 offset:360
	ds_read_b32 v97, v185 offset:488
	ds_read_b32 v98, v185 offset:364
	ds_read_b32 v99, v185 offset:492
	s_waitcnt lgkmcnt(0)
	v_lshl_add_u32 v66, v170, 2, s25
	v_lshl_add_u32 v67, v169, 10, v66
	s_add_u32 s17, s66, s96
	v_mul_f32_e32 v16, v16, v68
	v_mul_f32_e32 v0, v0, v68
	v_fma_f32 v16, v48, v69, -v16
	v_fma_f32 v0, v32, v69, -v0
	ds_write2_b32 v67, v16, v0 offset1:32
	v_lshl_add_u32 v32, v172, 8, v66
	s_addc_u32 s18, s67, s97
	s_lshl_b64 s[14:15], s[70:71], 2
	v_mul_f32_e32 v17, v17, v70
	v_mul_f32_e32 v0, v1, v70
	v_fma_f32 v1, v49, v71, -v17
	v_fma_f32 v0, v33, v71, -v0
	ds_write2_b32 v32, v1, v0 offset0:64 offset1:96
	s_add_u32 s14, s17, s14
	s_addc_u32 s15, s18, s15
	s_mov_b32 s8, 0x3c800000
	v_mul_f32_e32 v16, v18, v72
	v_mul_f32_e32 v0, v2, v72
	v_fma_f32 v2, v50, v73, -v16
	v_fma_f32 v0, v34, v73, -v0
	ds_write2_b32 v32, v2, v0 offset0:128 offset1:160
	s_mov_b64 s[38:39], 0x7200000
	s_mov_b64 s[36:37], 0
	v_mul_f32_e32 v2, v19, v74
	v_mul_f32_e32 v0, v3, v74
	v_fma_f32 v2, v51, v75, -v2
	v_fma_f32 v0, v35, v75, -v0
	ds_write2_b32 v32, v2, v0 offset0:192 offset1:224
	v_add_u32_e32 v2, 0x800, v32
	v_mul_f32_e32 v3, v20, v76
	v_mul_f32_e32 v0, v4, v76
	v_fma_f32 v3, v52, v77, -v3
	v_fma_f32 v0, v36, v77, -v0
	ds_write2_b32 v2, v3, v0 offset1:32
	v_mul_f32_e32 v3, v21, v78
	v_mul_f32_e32 v0, v5, v78
	v_fma_f32 v3, v53, v79, -v3
	v_fma_f32 v0, v37, v79, -v0
	ds_write2_b32 v2, v3, v0 offset0:64 offset1:96
	v_mul_f32_e32 v3, v22, v80
	v_mul_f32_e32 v0, v6, v80
	v_fma_f32 v3, v54, v81, -v3
	v_fma_f32 v0, v38, v81, -v0
	ds_write2_b32 v2, v3, v0 offset0:128 offset1:160
	v_mul_f32_e32 v3, v23, v82
	v_mul_f32_e32 v0, v7, v82
	v_fma_f32 v3, v55, v83, -v3
	v_fma_f32 v0, v39, v83, -v0
	ds_write2_b32 v2, v3, v0 offset0:192 offset1:224
	v_add_u32_e32 v2, 0x1000, v32
	v_mul_f32_e32 v3, v24, v84
	v_mul_f32_e32 v0, v8, v84
	v_fma_f32 v3, v56, v85, -v3
	v_fma_f32 v0, v40, v85, -v0
	ds_write2_b32 v2, v3, v0 offset1:32
	v_mul_f32_e32 v3, v25, v86
	v_mul_f32_e32 v0, v9, v86
	v_fma_f32 v3, v57, v87, -v3
	v_fma_f32 v0, v41, v87, -v0
	ds_write2_b32 v2, v3, v0 offset0:64 offset1:96
	v_mov_b64_e32 v[24:25], s[84:85]
	v_mul_f32_e32 v3, v26, v88
	v_mul_f32_e32 v0, v10, v88
	v_fma_f32 v3, v58, v89, -v3
	v_fma_f32 v0, v42, v89, -v0
	ds_write2_b32 v2, v3, v0 offset0:128 offset1:160
	v_mul_f32_e32 v3, v27, v90
	v_mul_f32_e32 v0, v11, v90
	v_fma_f32 v3, v59, v91, -v3
	v_fma_f32 v0, v43, v91, -v0
	ds_write2_b32 v2, v3, v0 offset0:192 offset1:224
	v_add_u32_e32 v2, 0x1800, v32
	v_mul_f32_e32 v3, v28, v92
	v_mul_f32_e32 v0, v12, v92
	v_fma_f32 v3, v60, v93, -v3
	v_fma_f32 v0, v44, v93, -v0
	ds_write2_b32 v2, v3, v0 offset1:32
	v_mul_f32_e32 v3, v29, v94
	v_mul_f32_e32 v0, v13, v94
	v_fma_f32 v3, v61, v95, -v3
	v_fma_f32 v0, v45, v95, -v0
	ds_write2_b32 v2, v3, v0 offset0:64 offset1:96
	v_lshlrev_b32_e32 v3, 3, v168
	v_and_b32_e32 v8, 56, v3
	v_lshlrev_b32_e32 v9, 2, v8
	v_add_u32_e32 v48, s25, v9
	v_mul_f32_e32 v4, v30, v97
	v_mul_f32_e32 v1, v14, v97
	v_fma_f32 v4, v62, v96, -v4
	v_fma_f32 v0, v46, v96, -v1
	ds_write2_b32 v2, v4, v0 offset0:128 offset1:160
	v_lshrrev_b32_e32 v46, 3, v167
	v_lshlrev_b32_e32 v128, 1, v8
	v_lshl_add_u32 v8, v46, 8, v48
	v_or_b32_e32 v52, 16, v46
	v_mul_f32_e32 v3, v31, v99
	v_mul_f32_e32 v1, v15, v99
	v_fma_f32 v3, v63, v98, -v3
	v_fma_f32 v0, v47, v98, -v1
	ds_write2_b32 v2, v3, v0 offset0:192 offset1:224
	s_waitcnt lgkmcnt(0)
	global_load_dwordx4 v[4:7], v9, s[14:15]
	global_load_dwordx4 v[0:3], v9, s[14:15] offset:16
	v_or_b32_e32 v47, 8, v46
	v_lshl_add_u32 v9, v47, 8, v48
	ds_read_b128 v[20:23], v8
	ds_read_b128 v[16:19], v8 offset:16
	ds_read_b128 v[12:15], v9
	ds_read_b128 v[8:11], v9 offset:16
	s_lshl_b64 s[14:15], s[50:51], 11
	s_add_u32 s14, s48, s14
	s_waitcnt lgkmcnt(3)
	v_pk_mul_f32 v[34:35], v[20:21], v[20:21]
	s_waitcnt lgkmcnt(1)
	v_pk_mul_f32 v[42:43], v[12:13], v[12:13]
	v_pk_mul_f32 v[32:33], v[22:23], v[22:23]
	v_pk_mul_f32 v[40:41], v[14:15], v[14:15]
	v_mov_b32_e32 v44, v42
	v_mov_b32_e32 v45, v34
	v_mov_b32_e32 v34, v43
	v_mov_b32_e32 v42, v40
	v_mov_b32_e32 v43, v32
	v_pk_add_f32 v[34:35], v[44:45], v[34:35]
	v_pk_mul_f32 v[30:31], v[16:17], v[16:17]
	s_waitcnt lgkmcnt(0)
; __device__ __forceinline__ unsigned cvtpk_s(float lo, float hi) { f32x2_t v = {lo, hi}; bf16x2_t b = __builtin_convertvector(v, bf16x2_t); return __builtin_bit_cast(unsigned, b); }
; __device__ __forceinline__ float sum8f(float x) { x += dppf<0xB1>(x); x += dppf<0x4E>(x); x += dppf<0x141>(x); return x; }
; #define x (arg_in(0))
;     ...
;     const int ch = lane & 7;
;     const float4 g0 = *(const float4*)(gsub + ch * 8), g1 = *(const float4*)(gsub + ch * 8 + 4);
; #pragma unroll
;     for (int i = 0; i < 4; ++i) { const int row = i * 8 + (lane >> 3);
;         const float4 a = *(const float4*)(stg + row * 64 + ch * 8), c = *(const float4*)(stg + row * 64 + ch * 8 + 4);
;         float ss = a.x * a.x + a.y * a.y + a.z * a.z + a.w * a.w + c.x * c.x + c.y * c.y + c.z * c.z + c.w * c.w;
;         ss = sum8f(ss);
;         const float rn = rsqrtf(ss * (1.f / 64.f) + EPS) * oscale;
;         u32x4 w; w.x = cvtpk_s(a.x * rn * g0.x, a.y * rn * g0.y); w.y = cvtpk_s(a.z * rn * g0.z, a.w * rn * g0.w); w.z = cvtpk_s(c.x * rn * g1.x, c.y * rn * g1.y); w.w = cvtpk_s(c.z * rn * g1.z, c.w * rn * g1.w);
;         *(u32x4*)(Ow + (long)row * D + ch * 8) = w; }
	v_pk_mul_f32 v[38:39], v[8:9], v[8:9]
	v_mov_b32_e32 v32, v41
	v_pk_add_f32 v[34:35], v[34:35], v[42:43]
	v_mov_b32_e32 v40, v38
	v_mov_b32_e32 v41, v30
	v_pk_add_f32 v[32:33], v[34:35], v[32:33]
	v_pk_mul_f32 v[26:27], v[18:19], v[18:19]
	v_pk_mul_f32 v[36:37], v[10:11], v[10:11]
	v_mov_b32_e32 v30, v39
	v_pk_add_f32 v[32:33], v[32:33], v[40:41]
	v_mov_b32_e32 v38, v36
	v_mov_b32_e32 v39, v26
	v_pk_add_f32 v[30:31], v[32:33], v[30:31]
	v_mov_b32_e32 v26, v37
	v_pk_add_f32 v[30:31], v[30:31], v[38:39]
	s_addc_u32 s15, s49, s15
	v_pk_add_f32 v[26:27], v[30:31], v[26:27]
	s_add_u32 s14, s14, s72
	v_mov_b32_e32 v31, v27
	v_mov_b32_e32 v30, v26
	s_addc_u32 s15, s15, s73
	v_mov_b32_dpp v31, v31 quad_perm:[1,0,3,2] row_mask:0xf bank_mask:0xf
	v_mov_b32_dpp v30, v30 quad_perm:[1,0,3,2] row_mask:0xf bank_mask:0xf
	v_pk_add_f32 v[26:27], v[26:27], v[30:31]
	v_lshl_add_u64 v[28:29], s[14:15], 0, v[128:129]
	v_mov_b32_e32 v31, v27
	v_mov_b32_e32 v30, v26
	v_lshlrev_b32_e32 v128, 11, v46
	v_mov_b32_dpp v31, v31 quad_perm:[2,3,0,1] row_mask:0xf bank_mask:0xf
	v_mov_b32_dpp v30, v30 quad_perm:[2,3,0,1] row_mask:0xf bank_mask:0xf
	v_pk_add_f32 v[26:27], v[26:27], v[30:31]
	v_lshl_add_u64 v[28:29], v[28:29], 0, s[38:39]
	v_mov_b32_e32 v31, v27
	v_mov_b32_e32 v30, v26
	v_or_b32_e32 v53, 24, v46
	v_mov_b32_dpp v31, v31 row_half_mirror row_mask:0xf bank_mask:0xf
	v_mov_b32_dpp v30, v30 row_half_mirror row_mask:0xf bank_mask:0xf
	v_pk_add_f32 v[26:27], v[26:27], v[30:31]
	s_nop 0
	v_pk_fma_f32 v[26:27], v[26:27], s[8:9], v[24:25] op_sel_hi:[1,0,0]
	s_nop 0
	v_mul_f32_e32 v30, 0x4b800000, v27
	v_cmp_gt_f32_e32 vcc, s57, v27
	v_mul_f32_e32 v34, 0x4b800000, v26
	s_nop 0
	v_cndmask_b32_e32 v27, v27, v30, vcc
	v_rsq_f32_e32 v27, v27
	v_lshl_add_u64 v[30:31], v[28:29], 0, v[128:129]
	v_lshlrev_b32_e32 v128, 11, v47
	v_mul_f32_e32 v32, 0x45800000, v27
	v_cndmask_b32_e32 v27, v27, v32, vcc
	v_mul_f32_e32 v32, v165, v27
	v_pk_mul_f32 v[20:21], v[20:21], v[32:33] op_sel_hi:[1,0]
	v_pk_mul_f32 v[22:23], v[22:23], v[32:33] op_sel_hi:[1,0]
	v_pk_mul_f32 v[16:17], v[16:17], v[32:33] op_sel_hi:[1,0]
	v_pk_mul_f32 v[32:33], v[18:19], v[32:33] op_sel_hi:[1,0]
	v_cmp_gt_f32_e32 vcc, s57, v26
	s_waitcnt vmcnt(1)
	v_pk_mul_f32 v[18:19], v[4:5], v[20:21]
	v_pk_mul_f32 v[20:21], v[6:7], v[22:23]
	s_waitcnt vmcnt(0)
	v_pk_mul_f32 v[22:23], v[0:1], v[16:17]
	v_cvt_pk_bf16_f32 v16, v18, v19
	v_cndmask_b32_e32 v19, v26, v34, vcc
	v_cvt_pk_bf16_f32 v18, v22, v23
	v_rsq_f32_e32 v22, v19
	v_cvt_pk_bf16_f32 v17, v20, v21
	v_pk_mul_f32 v[20:21], v[2:3], v[32:33]
	v_lshl_add_u64 v[26:27], v[28:29], 0, v[128:129]
	v_cvt_pk_bf16_f32 v19, v20, v21
	global_store_dwordx4 v[30:31], v[16:19], off
	v_lshl_add_u32 v30, v53, 8, v48
	v_lshlrev_b32_e32 v128, 11, v52
	v_mul_f32_e32 v16, 0x45800000, v22
	v_cndmask_b32_e32 v16, v22, v16, vcc
	v_mul_f32_e32 v16, v165, v16
	v_pk_mul_f32 v[12:13], v[12:13], v[16:17] op_sel_hi:[1,0]
	v_pk_mul_f32 v[14:15], v[14:15], v[16:17] op_sel_hi:[1,0]
	v_pk_mul_f32 v[8:9], v[8:9], v[16:17] op_sel_hi:[1,0]
	v_pk_mul_f32 v[12:13], v[4:5], v[12:13]
	v_pk_mul_f32 v[14:15], v[6:7], v[14:15]
	v_pk_mul_f32 v[8:9], v[0:1], v[8:9]
	v_cvt_pk_bf16_f32 v12, v12, v13
	v_cvt_pk_bf16_f32 v13, v14, v15
	v_cvt_pk_bf16_f32 v14, v8, v9
	v_pk_mul_f32 v[8:9], v[10:11], v[16:17] op_sel_hi:[1,0]
	v_lshl_add_u32 v16, v52, 8, v48
	v_pk_mul_f32 v[8:9], v[2:3], v[8:9]
	s_nop 0
	v_cvt_pk_bf16_f32 v15, v8, v9
	ds_read_b128 v[8:11], v16
	ds_read_b128 v[16:19], v16 offset:16
	ds_read_b128 v[20:23], v30
	ds_read_b128 v[30:33], v30 offset:16
	global_store_dwordx4 v[26:27], v[12:15], off
	s_waitcnt lgkmcnt(3)
; __device__ __forceinline__ unsigned cvtpk_s(float lo, float hi) { f32x2_t v = {lo, hi}; bf16x2_t b = __builtin_convertvector(v, bf16x2_t); return __builtin_bit_cast(unsigned, b); }
; __device__ __forceinline__ float sum8f(float x) { x += dppf<0xB1>(x); x += dppf<0x4E>(x); x += dppf<0x141>(x); return x; }
; #define x (arg_in(0))
;     ...
;     const int ch = lane & 7;
;     const float4 g0 = *(const float4*)(gsub + ch * 8), g1 = *(const float4*)(gsub + ch * 8 + 4);
; #pragma unroll
;     for (int i = 0; i < 4; ++i) { const int row = i * 8 + (lane >> 3);
;         const float4 a = *(const float4*)(stg + row * 64 + ch * 8), c = *(const float4*)(stg + row * 64 + ch * 8 + 4);
;         float ss = a.x * a.x + a.y * a.y + a.z * a.z + a.w * a.w + c.x * c.x + c.y * c.y + c.z * c.z + c.w * c.w;
;         ss = sum8f(ss);
;         const float rn = rsqrtf(ss * (1.f / 64.f) + EPS) * oscale;
;         u32x4 w; w.x = cvtpk_s(a.x * rn * g0.x, a.y * rn * g0.y); w.y = cvtpk_s(a.z * rn * g0.z, a.w * rn * g0.w); w.z = cvtpk_s(c.x * rn * g1.x, c.y * rn * g1.y); w.w = cvtpk_s(c.z * rn * g1.z, c.w * rn * g1.w);
;         *(u32x4*)(Ow + (long)row * D + ch * 8) = w; }
	v_pk_mul_f32 v[40:41], v[8:9], v[8:9]
	s_waitcnt lgkmcnt(1)
	v_pk_mul_f32 v[48:49], v[20:21], v[20:21]
	v_pk_mul_f32 v[38:39], v[10:11], v[10:11]
	v_pk_mul_f32 v[46:47], v[22:23], v[22:23]
	v_mov_b32_e32 v50, v48
	v_mov_b32_e32 v51, v40
	v_mov_b32_e32 v40, v49
	v_pk_add_f32 v[40:41], v[50:51], v[40:41]
	v_mov_b32_e32 v48, v46
	v_mov_b32_e32 v49, v38
	v_pk_mul_f32 v[36:37], v[16:17], v[16:17]
	s_waitcnt lgkmcnt(0)
	v_pk_mul_f32 v[44:45], v[30:31], v[30:31]
	v_pk_add_f32 v[40:41], v[40:41], v[48:49]
	v_mov_b32_e32 v38, v47
	v_pk_add_f32 v[38:39], v[40:41], v[38:39]
	v_mov_b32_e32 v40, v44
	v_mov_b32_e32 v41, v36
	v_pk_mul_f32 v[34:35], v[18:19], v[18:19]
	v_pk_mul_f32 v[42:43], v[32:33], v[32:33]
	v_pk_add_f32 v[38:39], v[38:39], v[40:41]
	v_mov_b32_e32 v36, v45
	v_pk_add_f32 v[36:37], v[38:39], v[36:37]
	v_mov_b32_e32 v38, v42
	v_mov_b32_e32 v39, v34
	v_pk_add_f32 v[36:37], v[36:37], v[38:39]
	v_mov_b32_e32 v34, v43
	v_pk_add_f32 v[34:35], v[36:37], v[34:35]
	v_lshl_add_u64 v[12:13], v[28:29], 0, v[128:129]
	v_mov_b32_e32 v37, v35
	v_mov_b32_e32 v36, v34
	v_lshlrev_b32_e32 v128, 11, v53
	v_mov_b32_dpp v37, v37 quad_perm:[1,0,3,2] row_mask:0xf bank_mask:0xf
	v_mov_b32_dpp v36, v36 quad_perm:[1,0,3,2] row_mask:0xf bank_mask:0xf
	v_pk_add_f32 v[34:35], v[34:35], v[36:37]
	s_nop 0
	v_mov_b32_e32 v37, v35
	v_mov_b32_e32 v36, v34
	s_nop 0
	v_mov_b32_dpp v37, v37 quad_perm:[2,3,0,1] row_mask:0xf bank_mask:0xf
	v_mov_b32_dpp v36, v36 quad_perm:[2,3,0,1] row_mask:0xf bank_mask:0xf
	v_pk_add_f32 v[34:35], v[34:35], v[36:37]
	s_nop 0
	v_mov_b32_e32 v37, v35
	v_mov_b32_e32 v36, v34
	s_nop 0
	v_mov_b32_dpp v37, v37 row_half_mirror row_mask:0xf bank_mask:0xf
	v_mov_b32_dpp v36, v36 row_half_mirror row_mask:0xf bank_mask:0xf
	v_pk_add_f32 v[34:35], v[34:35], v[36:37]
	s_nop 0
	v_pk_fma_f32 v[24:25], v[34:35], s[8:9], v[24:25] op_sel_hi:[1,0,0]
	s_nop 0
	v_mul_f32_e32 v34, 0x4b800000, v25
	v_cmp_gt_f32_e32 vcc, s57, v25
	s_nop 1
	v_cndmask_b32_e32 v25, v25, v34, vcc
	v_rsq_f32_e32 v25, v25
	s_nop 0
	v_mul_f32_e32 v14, 0x45800000, v25
	v_cndmask_b32_e32 v14, v25, v14, vcc
	v_mul_f32_e32 v14, v165, v14
	v_pk_mul_f32 v[8:9], v[8:9], v[14:15] op_sel_hi:[1,0]
	v_pk_mul_f32 v[10:11], v[10:11], v[14:15] op_sel_hi:[1,0]
	v_pk_mul_f32 v[8:9], v[4:5], v[8:9]
	v_pk_mul_f32 v[10:11], v[6:7], v[10:11]
	v_cvt_pk_bf16_f32 v8, v8, v9
	v_cvt_pk_bf16_f32 v9, v10, v11
	v_pk_mul_f32 v[10:11], v[16:17], v[14:15] op_sel_hi:[1,0]
	v_cmp_gt_f32_e32 vcc, s57, v24
	v_pk_mul_f32 v[10:11], v[0:1], v[10:11]
	v_pk_mul_f32 v[14:15], v[18:19], v[14:15] op_sel_hi:[1,0]
	v_cvt_pk_bf16_f32 v10, v10, v11
	v_mul_f32_e32 v11, 0x4b800000, v24
	v_cndmask_b32_e32 v11, v24, v11, vcc
	v_rsq_f32_e32 v16, v11
	v_pk_mul_f32 v[14:15], v[2:3], v[14:15]
	s_nop 0
	v_cvt_pk_bf16_f32 v11, v14, v15
	global_store_dwordx4 v[12:13], v[8:11], off
	s_nop 1
	v_mul_f32_e32 v8, 0x45800000, v16
	v_cndmask_b32_e32 v8, v16, v8, vcc
	v_mul_f32_e32 v8, v165, v8
	v_pk_mul_f32 v[10:11], v[20:21], v[8:9] op_sel_hi:[1,0]
	s_nop 0
	v_pk_mul_f32 v[4:5], v[4:5], v[10:11]
	v_pk_mul_f32 v[10:11], v[22:23], v[8:9] op_sel_hi:[1,0]
	v_cvt_pk_bf16_f32 v4, v4, v5
	v_pk_mul_f32 v[6:7], v[6:7], v[10:11]
	s_nop 0
	v_cvt_pk_bf16_f32 v5, v6, v7
	v_pk_mul_f32 v[6:7], v[30:31], v[8:9] op_sel_hi:[1,0]
	s_nop 0
	v_pk_mul_f32 v[0:1], v[0:1], v[6:7]
	s_nop 0
	v_cvt_pk_bf16_f32 v6, v0, v1
	v_pk_mul_f32 v[0:1], v[32:33], v[8:9] op_sel_hi:[1,0]
	s_nop 0
	v_pk_mul_f32 v[0:1], v[2:3], v[0:1]
	s_nop 0
	v_cvt_pk_bf16_f32 v7, v0, v1
	v_lshl_add_u64 v[0:1], v[28:29], 0, v[128:129]
	global_store_dwordx4 v[0:1], v[4:7], off
	s_waitcnt lgkmcnt(0)
